# GEMM mainloops: removed per-phase s_setprio flips (all waves prio 0); plus RET edits of v016
# speedup vs baseline: 1.0123x; 1.0081x over previous
; #define PG8_STAGE(bufoff, gbase, voff) do { _Pragma("unroll") for (int _i = 0; _i < 2; ++_i) \
;         __builtin_amdgcn_global_load_lds((const unsigned*)((const char*)(gbase) + (voff)[_i]), (LAS unsigned*)(lds + (bufoff) + ldsw + _i * 8192), 16, 0, 0); } while (0)
; #define PG8_LDA(dst, b, h) do { _Pragma("unroll") for (int m = 0; m < 4; ++m) _Pragma("unroll") for (int k = 0; k < 2; ++k) dst[m][k] = *(const LAS bf16x8*)(lds + PG8_SA(b, h) + aoff + m * 2048 + k * 1024); } while (0)
; #define PG8_LDB(dst, b, h) do { _Pragma("unroll") for (int n = 0; n < 2; ++n) _Pragma("unroll") for (int k = 0; k < 2; ++k) dst[n][k] = *(const LAS bf16x8*)(lds + PG8_SB(b, h) + boff + n * 2048 + k * 1024); } while (0)
; #define PG8_MMA(ai, bj, At, Bt) do { __builtin_amdgcn_s_setprio(1); _Pragma("unroll") for (int m = 0; m < 4; ++m) _Pragma("unroll") for (int n = 0; n < 2; ++n) _Pragma("unroll") for (int k = 0; k < 2; ++k) \
;         acc[ai][bj][m][n] = __builtin_amdgcn_mfma_f32_16x16x32_bf16(Bt[n][k], At[m][k], acc[ai][bj][m][n], 0, 0, 0); __builtin_amdgcn_s_setprio(0); } while (0)
; #define PG8_WAIT_L(n) asm volatile("s_waitcnt lgkmcnt(" #n ")" ::: "memory")
; #define PG8_BAR __builtin_amdgcn_s_barrier()
; #define PG8_SCHED __builtin_amdgcn_sched_barrier(0)
; template <class Epi, class Sched>
; __device__ __forceinline__ void gemm_phase(LAS unsigned char* lds, const Gemm g, const Sched& S, const Epi& E) {
;     ...
;             PG8_LDB(B0, 0, 0); PG8_SCHED; PG8_LDA(At, 0, 0); PG8_STAGE(PG8_SA(1, 1), a1 + hstep, voffA);
;             PG8_WAIT_L(8); PG8_BAR; PG8_WAIT_L(0); PG8_MMA(0, 0, At, B0); PG8_BAR; PG8_SCHED;
;             PG8_LDB(B1, 0, 1); PG8_STAGE(PG8_SB(0, 0), b2, voffB);
;             PG8_BAR; PG8_WAIT_L(0); PG8_MMA(0, 1, At, B1); PG8_BAR;
;             PG8_LDA(At, 0, 1); PG8_STAGE(PG8_SA(0, 0), a2, voffA);
;             PG8_BAR; PG8_WAIT_L(0); PG8_MMA(1, 0, At, B0); PG8_BAR; PG8_SCHED;
.LBB0_232:
	s_add_i32 s33, s29, 2
	s_add_u32 s30, s26, 0x80
	s_addc_u32 s31, s27, 0
	s_add_i32 s42, 0, 0x10000
	v_add_u32_e32 v140, s42, v191
	ds_read_b128 v[128:131], v140
	ds_read_b128 v[132:135], v140 offset:1024
	ds_read_b128 v[136:139], v140 offset:2048
	ds_read_b128 v[140:143], v140 offset:3072
	s_cmp_eq_u32 s76, s29
	s_cselect_b32 s31, s1, s31
	s_cselect_b32 s30, s0, s30
	s_cselect_b32 s35, s9, s25
	s_cselect_b32 s34, s8, s24
	v_lshl_add_u64 v[176:177], s[26:27], 0, v[194:195]
	s_add_i32 m0, s67, 0xc000
	ds_read_b128 v[144:147], v235
	ds_read_b128 v[148:151], v235 offset:1024
	ds_read_b128 v[152:155], v235 offset:2048
	ds_read_b128 v[156:159], v235 offset:3072
	ds_read_b128 v[160:163], v235 offset:4096
	ds_read_b128 v[164:167], v235 offset:5120
	ds_read_b128 v[168:171], v235 offset:6144
	ds_read_b128 v[172:175], v235 offset:7168
	global_load_lds_dwordx4 v[176:177], off
	v_lshl_add_u64 v[176:177], s[26:27], 0, v[192:193]
	s_add_i32 m0, s67, 0xe000
	s_nop 0
	global_load_lds_dwordx4 v[176:177], off
	s_waitcnt lgkmcnt(8)
	s_barrier
	s_waitcnt lgkmcnt(0)
	s_waitcnt lgkmcnt(0)
	v_mfma_f32_16x16x32_bf16 v[120:123], v[128:131], v[144:147], v[120:123]
	v_mfma_f32_16x16x32_bf16 v[112:115], v[136:139], v[144:147], v[112:115]
	v_mfma_f32_16x16x32_bf16 v[104:107], v[128:131], v[152:155], v[104:107]
	v_mfma_f32_16x16x32_bf16 v[96:99], v[136:139], v[152:155], v[96:99]
	v_mfma_f32_16x16x32_bf16 v[88:91], v[128:131], v[160:163], v[88:91]
	v_mfma_f32_16x16x32_bf16 v[80:83], v[136:139], v[160:163], v[80:83]
	v_mfma_f32_16x16x32_bf16 v[72:75], v[128:131], v[168:171], v[72:75]
	v_mfma_f32_16x16x32_bf16 v[64:67], v[136:139], v[168:171], v[64:67]
	v_mfma_f32_16x16x32_bf16 v[120:123], v[132:135], v[148:151], v[120:123]
	v_mfma_f32_16x16x32_bf16 v[112:115], v[140:143], v[148:151], v[112:115]
	v_mfma_f32_16x16x32_bf16 v[104:107], v[132:135], v[156:159], v[104:107]
	v_mfma_f32_16x16x32_bf16 v[96:99], v[140:143], v[156:159], v[96:99]
	v_mfma_f32_16x16x32_bf16 v[88:91], v[132:135], v[164:167], v[88:91]
	v_mfma_f32_16x16x32_bf16 v[80:83], v[140:143], v[164:167], v[80:83]
	v_mfma_f32_16x16x32_bf16 v[72:75], v[132:135], v[172:175], v[72:75]
	v_mfma_f32_16x16x32_bf16 v[64:67], v[140:143], v[172:175], v[64:67]
	s_barrier
	s_add_i32 s29, 0, 0x14000
	s_add_i32 s42, s42, s66
	v_add_u32_e32 v200, s29, v191
	v_lshl_add_u64 v[204:205], s[34:35], 0, v[188:189]
	s_mov_b32 m0, s42
	ds_read_b128 v[176:179], v200
	ds_read_b128 v[180:183], v200 offset:1024
	ds_read_b128 v[196:199], v200 offset:2048
	ds_read_b128 v[200:203], v200 offset:3072
	global_load_lds_dwordx4 v[204:205], off
	v_lshl_add_u64 v[206:207], s[34:35], 0, v[184:185]
	s_add_i32 m0, s42, 0x2000
	s_nop 0
	global_load_lds_dwordx4 v[206:207], off
	s_barrier
	s_waitcnt lgkmcnt(0)
	s_waitcnt lgkmcnt(0)
	v_mfma_f32_16x16x32_bf16 v[124:127], v[176:179], v[144:147], v[124:127]
	v_mfma_f32_16x16x32_bf16 v[116:119], v[196:199], v[144:147], v[116:119]
	v_mfma_f32_16x16x32_bf16 v[108:111], v[176:179], v[152:155], v[108:111]
	v_mfma_f32_16x16x32_bf16 v[100:103], v[196:199], v[152:155], v[100:103]
	v_mfma_f32_16x16x32_bf16 v[92:95], v[176:179], v[160:163], v[92:95]
	v_mfma_f32_16x16x32_bf16 v[84:87], v[196:199], v[160:163], v[84:87]
	v_mfma_f32_16x16x32_bf16 v[76:79], v[176:179], v[168:171], v[76:79]
	v_mfma_f32_16x16x32_bf16 v[68:71], v[196:199], v[168:171], v[68:71]
	v_mfma_f32_16x16x32_bf16 v[124:127], v[180:183], v[148:151], v[124:127]
	v_mfma_f32_16x16x32_bf16 v[116:119], v[200:203], v[148:151], v[116:119]
	v_mfma_f32_16x16x32_bf16 v[108:111], v[180:183], v[156:159], v[108:111]
	v_mfma_f32_16x16x32_bf16 v[100:103], v[200:203], v[156:159], v[100:103]
	v_mfma_f32_16x16x32_bf16 v[92:95], v[180:183], v[164:167], v[92:95]
	v_mfma_f32_16x16x32_bf16 v[84:87], v[200:203], v[164:167], v[84:87]
	v_mfma_f32_16x16x32_bf16 v[76:79], v[180:183], v[172:175], v[76:79]
	v_mfma_f32_16x16x32_bf16 v[68:71], v[200:203], v[172:175], v[68:71]
	s_mov_b32 m0, s67
	v_lshl_add_u64 v[208:209], s[30:31], 0, v[188:189]
	s_barrier
	ds_read_b128 v[144:147], v235 offset:16384
	ds_read_b128 v[148:151], v235 offset:17408
	ds_read_b128 v[152:155], v235 offset:18432
	ds_read_b128 v[156:159], v235 offset:19456
	ds_read_b128 v[160:163], v235 offset:20480
	ds_read_b128 v[164:167], v235 offset:21504
	ds_read_b128 v[168:171], v235 offset:22528
	ds_read_b128 v[172:175], v235 offset:23552
	global_load_lds_dwordx4 v[208:209], off
	v_lshl_add_u64 v[210:211], s[30:31], 0, v[184:185]
	s_mov_b32 m0, s68
	s_nop 0
	global_load_lds_dwordx4 v[210:211], off
	s_barrier
	s_waitcnt lgkmcnt(0)
	s_waitcnt lgkmcnt(0)
	v_mfma_f32_16x16x32_bf16 v[56:59], v[128:131], v[144:147], v[56:59]
	v_mfma_f32_16x16x32_bf16 v[48:51], v[136:139], v[144:147], v[48:51]
	v_mfma_f32_16x16x32_bf16 v[40:43], v[128:131], v[152:155], v[40:43]
	v_mfma_f32_16x16x32_bf16 v[32:35], v[136:139], v[152:155], v[32:35]
	v_mfma_f32_16x16x32_bf16 v[24:27], v[128:131], v[160:163], v[24:27]
	v_mfma_f32_16x16x32_bf16 v[16:19], v[136:139], v[160:163], v[16:19]
	v_mfma_f32_16x16x32_bf16 v[8:11], v[128:131], v[168:171], v[8:11]
	v_mfma_f32_16x16x32_bf16 v[0:3], v[136:139], v[168:171], v[0:3]
	v_mfma_f32_16x16x32_bf16 v[56:59], v[132:135], v[148:151], v[56:59]
	v_mfma_f32_16x16x32_bf16 v[48:51], v[140:143], v[148:151], v[48:51]
	v_mfma_f32_16x16x32_bf16 v[40:43], v[132:135], v[156:159], v[40:43]
	v_mfma_f32_16x16x32_bf16 v[32:35], v[140:143], v[156:159], v[32:35]
	v_mfma_f32_16x16x32_bf16 v[24:27], v[132:135], v[164:167], v[24:27]
	v_mfma_f32_16x16x32_bf16 v[16:19], v[140:143], v[164:167], v[16:19]
	v_mfma_f32_16x16x32_bf16 v[8:11], v[132:135], v[172:175], v[8:11]
	v_mfma_f32_16x16x32_bf16 v[0:3], v[140:143], v[172:175], v[0:3]
	s_barrier
; #define PG8_STAGE(bufoff, gbase, voff) do { _Pragma("unroll") for (int _i = 0; _i < 2; ++_i) \
;         __builtin_amdgcn_global_load_lds((const unsigned*)((const char*)(gbase) + (voff)[_i]), (LAS unsigned*)(lds + (bufoff) + ldsw + _i * 8192), 16, 0, 0); } while (0)
; #define PG8_LDA(dst, b, h) do { _Pragma("unroll") for (int m = 0; m < 4; ++m) _Pragma("unroll") for (int k = 0; k < 2; ++k) dst[m][k] = *(const LAS bf16x8*)(lds + PG8_SA(b, h) + aoff + m * 2048 + k * 1024); } while (0)
; #define PG8_LDB(dst, b, h) do { _Pragma("unroll") for (int n = 0; n < 2; ++n) _Pragma("unroll") for (int k = 0; k < 2; ++k) dst[n][k] = *(const LAS bf16x8*)(lds + PG8_SB(b, h) + boff + n * 2048 + k * 1024); } while (0)
; #define PG8_MMA(ai, bj, At, Bt) do { __builtin_amdgcn_s_setprio(1); _Pragma("unroll") for (int m = 0; m < 4; ++m) _Pragma("unroll") for (int n = 0; n < 2; ++n) _Pragma("unroll") for (int k = 0; k < 2; ++k) \
;         acc[ai][bj][m][n] = __builtin_amdgcn_mfma_f32_16x16x32_bf16(Bt[n][k], At[m][k], acc[ai][bj][m][n], 0, 0, 0); __builtin_amdgcn_s_setprio(0); } while (0)
; #define PG8_WAIT_V(n) asm volatile("s_waitcnt vmcnt(" #n ")" ::: "memory")
; #define PG8_WAIT_L(n) asm volatile("s_waitcnt lgkmcnt(" #n ")" ::: "memory")
; #define PG8_BAR __builtin_amdgcn_s_barrier()
; #define PG8_SCHED __builtin_amdgcn_sched_barrier(0)
; template <class Epi, class Sched>
; __device__ __forceinline__ void gemm_phase(LAS unsigned char* lds, const Gemm g, const Sched& S, const Epi& E) {
;     ...
;             PG8_STAGE(PG8_SB(0, 1), b2 + hstep, voffB);
;             PG8_WAIT_V(6); PG8_BAR; PG8_MMA(1, 1, At, B1); PG8_BAR;
;             PG8_LDB(B0, 1, 0); PG8_SCHED; PG8_LDA(At, 1, 0); PG8_STAGE(PG8_SA(0, 1), a2 + hstep, voffA);
;             PG8_WAIT_L(8); PG8_BAR; PG8_WAIT_L(0); PG8_MMA(0, 0, At, B0); PG8_BAR; PG8_SCHED;
;             PG8_LDB(B1, 1, 1); PG8_STAGE(PG8_SB(1, 0), b3, voffB);
	s_add_u32 s34, s34, s12
	s_addc_u32 s35, s35, s13
	s_add_i32 s29, s29, s66
	v_lshl_add_u64 v[212:213], s[34:35], 0, v[188:189]
	s_mov_b32 m0, s29
	v_lshl_add_u64 v[214:215], s[34:35], 0, v[184:185]
	global_load_lds_dwordx4 v[212:213], off
	s_add_i32 m0, s29, 0x2000
	s_nop 0
	global_load_lds_dwordx4 v[214:215], off
	s_waitcnt vmcnt(6)
	s_barrier
	v_mfma_f32_16x16x32_bf16 v[60:63], v[176:179], v[144:147], v[60:63]
	v_mfma_f32_16x16x32_bf16 v[52:55], v[196:199], v[144:147], v[52:55]
	v_mfma_f32_16x16x32_bf16 v[44:47], v[176:179], v[152:155], v[44:47]
	v_mfma_f32_16x16x32_bf16 v[36:39], v[196:199], v[152:155], v[36:39]
	v_mfma_f32_16x16x32_bf16 v[28:31], v[176:179], v[160:163], v[28:31]
	v_mfma_f32_16x16x32_bf16 v[20:23], v[196:199], v[160:163], v[20:23]
	v_mfma_f32_16x16x32_bf16 v[12:15], v[176:179], v[168:171], v[12:15]
	v_mfma_f32_16x16x32_bf16 v[4:7], v[196:199], v[168:171], v[4:7]
	v_mfma_f32_16x16x32_bf16 v[60:63], v[180:183], v[148:151], v[60:63]
	v_mfma_f32_16x16x32_bf16 v[52:55], v[200:203], v[148:151], v[52:55]
	v_mfma_f32_16x16x32_bf16 v[44:47], v[180:183], v[156:159], v[44:47]
	v_mfma_f32_16x16x32_bf16 v[36:39], v[200:203], v[156:159], v[36:39]
	v_mfma_f32_16x16x32_bf16 v[28:31], v[180:183], v[164:167], v[28:31]
	v_mfma_f32_16x16x32_bf16 v[20:23], v[200:203], v[164:167], v[20:23]
	v_mfma_f32_16x16x32_bf16 v[12:15], v[180:183], v[172:175], v[12:15]
	v_mfma_f32_16x16x32_bf16 v[4:7], v[200:203], v[172:175], v[4:7]
	s_add_i32 s29, 0, 0x18000
	v_add_u32_e32 v140, s29, v191
	s_barrier
	ds_read_b128 v[128:131], v140
	ds_read_b128 v[132:135], v140 offset:1024
	ds_read_b128 v[136:139], v140 offset:2048
	ds_read_b128 v[140:143], v140 offset:3072
	s_add_u32 s30, s30, s12
	s_addc_u32 s31, s31, s13
	s_mov_b32 m0, s69
	v_lshl_add_u64 v[176:177], s[30:31], 0, v[188:189]
	ds_read_b128 v[144:147], v235 offset:32768
	ds_read_b128 v[148:151], v235 offset:33792
	ds_read_b128 v[152:155], v235 offset:34816
	ds_read_b128 v[156:159], v235 offset:35840
	ds_read_b128 v[160:163], v235 offset:36864
	ds_read_b128 v[164:167], v235 offset:37888
	ds_read_b128 v[168:171], v235 offset:38912
	ds_read_b128 v[172:175], v235 offset:39936
	global_load_lds_dwordx4 v[176:177], off
	v_lshl_add_u64 v[176:177], s[30:31], 0, v[184:185]
	s_mov_b32 m0, s70
	s_nop 0
	global_load_lds_dwordx4 v[176:177], off
	s_waitcnt lgkmcnt(8)
	s_barrier
	s_waitcnt lgkmcnt(0)
	s_waitcnt lgkmcnt(0)
	v_mfma_f32_16x16x32_bf16 v[120:123], v[128:131], v[144:147], v[120:123]
	v_mfma_f32_16x16x32_bf16 v[112:115], v[136:139], v[144:147], v[112:115]
	v_mfma_f32_16x16x32_bf16 v[104:107], v[128:131], v[152:155], v[104:107]
	v_mfma_f32_16x16x32_bf16 v[96:99], v[136:139], v[152:155], v[96:99]
	v_mfma_f32_16x16x32_bf16 v[88:91], v[128:131], v[160:163], v[88:91]
	v_mfma_f32_16x16x32_bf16 v[80:83], v[136:139], v[160:163], v[80:83]
	v_mfma_f32_16x16x32_bf16 v[72:75], v[128:131], v[168:171], v[72:75]
	v_mfma_f32_16x16x32_bf16 v[64:67], v[136:139], v[168:171], v[64:67]
	v_mfma_f32_16x16x32_bf16 v[120:123], v[132:135], v[148:151], v[120:123]
	v_mfma_f32_16x16x32_bf16 v[112:115], v[140:143], v[148:151], v[112:115]
	v_mfma_f32_16x16x32_bf16 v[104:107], v[132:135], v[156:159], v[104:107]
	v_mfma_f32_16x16x32_bf16 v[96:99], v[140:143], v[156:159], v[96:99]
	v_mfma_f32_16x16x32_bf16 v[88:91], v[132:135], v[164:167], v[88:91]
	v_mfma_f32_16x16x32_bf16 v[80:83], v[140:143], v[164:167], v[80:83]
	v_mfma_f32_16x16x32_bf16 v[72:75], v[132:135], v[172:175], v[72:75]
	v_mfma_f32_16x16x32_bf16 v[64:67], v[140:143], v[172:175], v[64:67]
	s_barrier
	s_add_i32 s30, 0, 0x1c000
	s_add_i32 s29, s29, s66
	v_add_u32_e32 v200, s30, v191
	v_lshl_add_u64 v[204:205], v[204:205], 0, s[64:65]
	s_mov_b32 m0, s29
	ds_read_b128 v[176:179], v200
	ds_read_b128 v[180:183], v200 offset:1024
	ds_read_b128 v[196:199], v200 offset:2048
	ds_read_b128 v[200:203], v200 offset:3072
	global_load_lds_dwordx4 v[204:205], off
	v_lshl_add_u64 v[204:205], v[206:207], 0, s[64:65]
	s_add_i32 m0, s29, 0x2000
	s_nop 0
	global_load_lds_dwordx4 v[204:205], off
	s_barrier
; #define PG8_STAGE(bufoff, gbase, voff) do { _Pragma("unroll") for (int _i = 0; _i < 2; ++_i) \
;         __builtin_amdgcn_global_load_lds((const unsigned*)((const char*)(gbase) + (voff)[_i]), (LAS unsigned*)(lds + (bufoff) + ldsw + _i * 8192), 16, 0, 0); } while (0)
; #define PG8_LDA(dst, b, h) do { _Pragma("unroll") for (int m = 0; m < 4; ++m) _Pragma("unroll") for (int k = 0; k < 2; ++k) dst[m][k] = *(const LAS bf16x8*)(lds + PG8_SA(b, h) + aoff + m * 2048 + k * 1024); } while (0)
; #define PG8_MMA(ai, bj, At, Bt) do { __builtin_amdgcn_s_setprio(1); _Pragma("unroll") for (int m = 0; m < 4; ++m) _Pragma("unroll") for (int n = 0; n < 2; ++n) _Pragma("unroll") for (int k = 0; k < 2; ++k) \
;         acc[ai][bj][m][n] = __builtin_amdgcn_mfma_f32_16x16x32_bf16(Bt[n][k], At[m][k], acc[ai][bj][m][n], 0, 0, 0); __builtin_amdgcn_s_setprio(0); } while (0)
; #define PG8_WAIT_V(n) asm volatile("s_waitcnt vmcnt(" #n ")" ::: "memory")
; #define PG8_WAIT_L(n) asm volatile("s_waitcnt lgkmcnt(" #n ")" ::: "memory")
; #define PG8_BAR __builtin_amdgcn_s_barrier()
; #define PG8_SCHED __builtin_amdgcn_sched_barrier(0)
; template <class Epi, class Sched>
; __device__ __forceinline__ void gemm_phase(LAS unsigned char* lds, const Gemm g, const Sched& S, const Epi& E) {
;     ...
;             PG8_BAR; PG8_WAIT_L(0); PG8_MMA(0, 1, At, B1); PG8_BAR;
;             PG8_LDA(At, 1, 1); PG8_STAGE(PG8_SA(1, 0), a3, voffA);
;             PG8_BAR; PG8_WAIT_L(0); PG8_MMA(1, 0, At, B0); PG8_BAR; PG8_SCHED;
;             PG8_STAGE(PG8_SB(1, 1), b3 + hstep, voffB);
;             PG8_WAIT_V(6); PG8_BAR; PG8_MMA(1, 1, At, B1); PG8_BAR;
;         }
	s_waitcnt lgkmcnt(0)
	s_waitcnt lgkmcnt(0)
	v_mfma_f32_16x16x32_bf16 v[124:127], v[176:179], v[144:147], v[124:127]
	v_mfma_f32_16x16x32_bf16 v[116:119], v[196:199], v[144:147], v[116:119]
	v_mfma_f32_16x16x32_bf16 v[108:111], v[176:179], v[152:155], v[108:111]
	v_mfma_f32_16x16x32_bf16 v[100:103], v[196:199], v[152:155], v[100:103]
	v_mfma_f32_16x16x32_bf16 v[92:95], v[176:179], v[160:163], v[92:95]
	v_mfma_f32_16x16x32_bf16 v[84:87], v[196:199], v[160:163], v[84:87]
	v_mfma_f32_16x16x32_bf16 v[76:79], v[176:179], v[168:171], v[76:79]
	v_mfma_f32_16x16x32_bf16 v[68:71], v[196:199], v[168:171], v[68:71]
	v_mfma_f32_16x16x32_bf16 v[124:127], v[180:183], v[148:151], v[124:127]
	v_mfma_f32_16x16x32_bf16 v[116:119], v[200:203], v[148:151], v[116:119]
	v_mfma_f32_16x16x32_bf16 v[108:111], v[180:183], v[156:159], v[108:111]
	v_mfma_f32_16x16x32_bf16 v[100:103], v[200:203], v[156:159], v[100:103]
	v_mfma_f32_16x16x32_bf16 v[92:95], v[180:183], v[164:167], v[92:95]
	v_mfma_f32_16x16x32_bf16 v[84:87], v[200:203], v[164:167], v[84:87]
	v_mfma_f32_16x16x32_bf16 v[76:79], v[180:183], v[172:175], v[76:79]
	v_mfma_f32_16x16x32_bf16 v[68:71], v[200:203], v[172:175], v[68:71]
	s_mov_b32 m0, s18
	v_lshl_add_u64 v[204:205], v[208:209], 0, s[64:65]
	s_barrier
	ds_read_b128 v[144:147], v235 offset:49152
	ds_read_b128 v[148:151], v235 offset:50176
	ds_read_b128 v[152:155], v235 offset:51200
	ds_read_b128 v[156:159], v235 offset:52224
	ds_read_b128 v[160:163], v235 offset:53248
	ds_read_b128 v[164:167], v235 offset:54272
	ds_read_b128 v[168:171], v235 offset:55296
	ds_read_b128 v[172:175], v235 offset:56320
	global_load_lds_dwordx4 v[204:205], off
	v_lshl_add_u64 v[204:205], v[210:211], 0, s[64:65]
	s_mov_b32 m0, s75
	s_nop 0
	global_load_lds_dwordx4 v[204:205], off
	s_barrier
	s_waitcnt lgkmcnt(0)
	s_waitcnt lgkmcnt(0)
	v_mfma_f32_16x16x32_bf16 v[56:59], v[128:131], v[144:147], v[56:59]
	v_mfma_f32_16x16x32_bf16 v[48:51], v[136:139], v[144:147], v[48:51]
	v_mfma_f32_16x16x32_bf16 v[40:43], v[128:131], v[152:155], v[40:43]
	v_mfma_f32_16x16x32_bf16 v[32:35], v[136:139], v[152:155], v[32:35]
	v_mfma_f32_16x16x32_bf16 v[24:27], v[128:131], v[160:163], v[24:27]
	v_mfma_f32_16x16x32_bf16 v[16:19], v[136:139], v[160:163], v[16:19]
	v_mfma_f32_16x16x32_bf16 v[8:11], v[128:131], v[168:171], v[8:11]
	v_mfma_f32_16x16x32_bf16 v[0:3], v[136:139], v[168:171], v[0:3]
	v_mfma_f32_16x16x32_bf16 v[56:59], v[132:135], v[148:151], v[56:59]
	v_mfma_f32_16x16x32_bf16 v[48:51], v[140:143], v[148:151], v[48:51]
	v_mfma_f32_16x16x32_bf16 v[40:43], v[132:135], v[156:159], v[40:43]
	v_mfma_f32_16x16x32_bf16 v[32:35], v[140:143], v[156:159], v[32:35]
	v_mfma_f32_16x16x32_bf16 v[24:27], v[132:135], v[164:167], v[24:27]
	v_mfma_f32_16x16x32_bf16 v[16:19], v[140:143], v[164:167], v[16:19]
	v_mfma_f32_16x16x32_bf16 v[8:11], v[132:135], v[172:175], v[8:11]
	v_mfma_f32_16x16x32_bf16 v[0:3], v[140:143], v[172:175], v[0:3]
	s_barrier
	s_add_i32 s29, s30, s66
	v_lshl_add_u64 v[128:129], v[212:213], 0, s[64:65]
	s_mov_b32 m0, s29
	s_nop 0
	global_load_lds_dwordx4 v[128:129], off
	v_lshl_add_u64 v[128:129], v[214:215], 0, s[64:65]
	s_add_i32 m0, s29, 0x2000
	s_nop 0
	global_load_lds_dwordx4 v[128:129], off
	s_waitcnt vmcnt(6)
	s_barrier
	v_mfma_f32_16x16x32_bf16 v[60:63], v[176:179], v[144:147], v[60:63]
	v_mfma_f32_16x16x32_bf16 v[52:55], v[196:199], v[144:147], v[52:55]
	v_mfma_f32_16x16x32_bf16 v[44:47], v[176:179], v[152:155], v[44:47]
	v_mfma_f32_16x16x32_bf16 v[36:39], v[196:199], v[152:155], v[36:39]
	v_mfma_f32_16x16x32_bf16 v[28:31], v[176:179], v[160:163], v[28:31]
	v_mfma_f32_16x16x32_bf16 v[20:23], v[196:199], v[160:163], v[20:23]
	v_mfma_f32_16x16x32_bf16 v[12:15], v[176:179], v[168:171], v[12:15]
	v_mfma_f32_16x16x32_bf16 v[4:7], v[196:199], v[168:171], v[4:7]
	v_mfma_f32_16x16x32_bf16 v[60:63], v[180:183], v[148:151], v[60:63]
	v_mfma_f32_16x16x32_bf16 v[52:55], v[200:203], v[148:151], v[52:55]
	v_mfma_f32_16x16x32_bf16 v[44:47], v[180:183], v[156:159], v[44:47]
	v_mfma_f32_16x16x32_bf16 v[36:39], v[200:203], v[156:159], v[36:39]
	v_mfma_f32_16x16x32_bf16 v[28:31], v[180:183], v[164:167], v[28:31]
	v_mfma_f32_16x16x32_bf16 v[20:23], v[200:203], v[164:167], v[20:23]
	v_mfma_f32_16x16x32_bf16 v[12:15], v[180:183], v[172:175], v[12:15]
	v_mfma_f32_16x16x32_bf16 v[4:7], v[200:203], v[172:175], v[4:7]
	s_add_u32 s24, s24, 0x100
	s_addc_u32 s25, s25, 0
	s_add_u32 s26, s26, 0x100
	s_addc_u32 s27, s27, 0
	s_cmp_ge_i32 s33, s74
	s_mov_b32 s29, s33
	s_barrier
	s_cbranch_scc0 .LBB0_232
	s_mov_b32 s42, s82
	s_branch .LBB0_235

; #define PG8_STAGE(bufoff, gbase, voff) do { _Pragma("unroll") for (int _i = 0; _i < 2; ++_i) \
;         __builtin_amdgcn_global_load_lds((const unsigned*)((const char*)(gbase) + (voff)[_i]), (LAS unsigned*)(lds + (bufoff) + ldsw + _i * 8192), 16, 0, 0); } while (0)
; #define PG8_LDA(dst, b, h) do { _Pragma("unroll") for (int m = 0; m < 4; ++m) _Pragma("unroll") for (int k = 0; k < 2; ++k) dst[m][k] = *(const LAS bf16x8*)(lds + PG8_SA(b, h) + aoff + m * 2048 + k * 1024); } while (0)
; #define PG8_LDB(dst, b, h) do { _Pragma("unroll") for (int n = 0; n < 2; ++n) _Pragma("unroll") for (int k = 0; k < 2; ++k) dst[n][k] = *(const LAS bf16x8*)(lds + PG8_SB(b, h) + boff + n * 2048 + k * 1024); } while (0)
; #define PG8_MMA(ai, bj, At, Bt) do { __builtin_amdgcn_s_setprio(1); _Pragma("unroll") for (int m = 0; m < 4; ++m) _Pragma("unroll") for (int n = 0; n < 2; ++n) _Pragma("unroll") for (int k = 0; k < 2; ++k) \
;         acc[ai][bj][m][n] = __builtin_amdgcn_mfma_f32_16x16x32_bf16(Bt[n][k], At[m][k], acc[ai][bj][m][n], 0, 0, 0); __builtin_amdgcn_s_setprio(0); } while (0)
; #define PG8_WAIT_L(n) asm volatile("s_waitcnt lgkmcnt(" #n ")" ::: "memory")
; #define PG8_BAR __builtin_amdgcn_s_barrier()
; #define PG8_SCHED __builtin_amdgcn_sched_barrier(0)
; template <class Epi, class Sched>
; __device__ __forceinline__ void gemm_phase(LAS unsigned char* lds, const Gemm g, const Sched& S, const Epi& E) {
;     ...
;             PG8_LDB(B0, 0, 0); PG8_SCHED; PG8_LDA(At, 0, 0); PG8_STAGE(PG8_SA(1, 1), a1 + hstep, voffA);
;             PG8_WAIT_L(8); PG8_BAR; PG8_WAIT_L(0); PG8_MMA(0, 0, At, B0); PG8_BAR; PG8_SCHED;
;             PG8_LDB(B1, 0, 1); PG8_STAGE(PG8_SB(0, 0), b2, voffB);
;             PG8_BAR; PG8_WAIT_L(0); PG8_MMA(0, 1, At, B1); PG8_BAR;
;             PG8_LDA(At, 0, 1); PG8_STAGE(PG8_SA(0, 0), a2, voffA);
;             PG8_BAR; PG8_WAIT_L(0); PG8_MMA(1, 0, At, B0); PG8_BAR; PG8_SCHED;
.LBB0_339:
	s_add_i32 s30, s4, 2
	s_add_u32 s28, s0, 0x80
	s_addc_u32 s5, s1, 0
	s_add_i32 s31, 0, 0x10000
	v_add_u32_e32 v140, s31, v214
	ds_read_b128 v[128:131], v140
	ds_read_b128 v[132:135], v140 offset:1024
	ds_read_b128 v[136:139], v140 offset:2048
	ds_read_b128 v[140:143], v140 offset:3072
	s_cmp_eq_u32 s66, s4
	s_cselect_b32 s4, s18, s28
	s_cselect_b32 s5, s19, s5
	s_cselect_b32 s29, s27, s76
	s_cselect_b32 s28, s26, s75
	v_lshl_add_u64 v[176:177], s[0:1], 0, v[200:201]
	s_add_i32 m0, s50, 0xc000
	ds_read_b128 v[144:147], v221
	ds_read_b128 v[148:151], v221 offset:1024
	ds_read_b128 v[152:155], v221 offset:2048
	ds_read_b128 v[156:159], v221 offset:3072
	ds_read_b128 v[160:163], v221 offset:4096
	ds_read_b128 v[164:167], v221 offset:5120
	ds_read_b128 v[168:171], v221 offset:6144
	ds_read_b128 v[172:175], v221 offset:7168
	global_load_lds_dwordx4 v[176:177], off
	v_lshl_add_u64 v[176:177], s[0:1], 0, v[198:199]
	s_add_i32 m0, s50, 0xe000
	s_nop 0
	global_load_lds_dwordx4 v[176:177], off
	s_waitcnt lgkmcnt(8)
	s_barrier
	s_waitcnt lgkmcnt(0)
	s_waitcnt lgkmcnt(0)
	v_mfma_f32_16x16x32_bf16 v[120:123], v[128:131], v[144:147], v[120:123]
	v_mfma_f32_16x16x32_bf16 v[112:115], v[136:139], v[144:147], v[112:115]
	v_mfma_f32_16x16x32_bf16 v[104:107], v[128:131], v[152:155], v[104:107]
	v_mfma_f32_16x16x32_bf16 v[96:99], v[136:139], v[152:155], v[96:99]
	v_mfma_f32_16x16x32_bf16 v[88:91], v[128:131], v[160:163], v[88:91]
	v_mfma_f32_16x16x32_bf16 v[80:83], v[136:139], v[160:163], v[80:83]
	v_mfma_f32_16x16x32_bf16 v[72:75], v[128:131], v[168:171], v[72:75]
	v_mfma_f32_16x16x32_bf16 v[64:67], v[136:139], v[168:171], v[64:67]
	v_mfma_f32_16x16x32_bf16 v[120:123], v[132:135], v[148:151], v[120:123]
	v_mfma_f32_16x16x32_bf16 v[112:115], v[140:143], v[148:151], v[112:115]
	v_mfma_f32_16x16x32_bf16 v[104:107], v[132:135], v[156:159], v[104:107]
	v_mfma_f32_16x16x32_bf16 v[96:99], v[140:143], v[156:159], v[96:99]
	v_mfma_f32_16x16x32_bf16 v[88:91], v[132:135], v[164:167], v[88:91]
	v_mfma_f32_16x16x32_bf16 v[80:83], v[140:143], v[164:167], v[80:83]
	v_mfma_f32_16x16x32_bf16 v[72:75], v[132:135], v[172:175], v[72:75]
	v_mfma_f32_16x16x32_bf16 v[64:67], v[140:143], v[172:175], v[64:67]
	s_barrier
	s_add_i32 s33, 0, 0x14000
	s_add_i32 s31, s31, s34
	v_add_u32_e32 v188, s33, v214
	v_lshl_add_u64 v[206:207], s[28:29], 0, v[192:193]
	s_mov_b32 m0, s31
	ds_read_b128 v[176:179], v188
	ds_read_b128 v[180:183], v188 offset:1024
	ds_read_b128 v[184:187], v188 offset:2048
	ds_read_b128 v[202:205], v188 offset:3072
	global_load_lds_dwordx4 v[206:207], off
	v_lshl_add_u64 v[208:209], s[28:29], 0, v[194:195]
	s_add_i32 m0, s31, 0x2000
	s_nop 0
	global_load_lds_dwordx4 v[208:209], off
	s_barrier
	s_waitcnt lgkmcnt(0)
	s_waitcnt lgkmcnt(0)
	v_mfma_f32_16x16x32_bf16 v[124:127], v[176:179], v[144:147], v[124:127]
	v_mfma_f32_16x16x32_bf16 v[116:119], v[184:187], v[144:147], v[116:119]
	v_mfma_f32_16x16x32_bf16 v[108:111], v[176:179], v[152:155], v[108:111]
	v_mfma_f32_16x16x32_bf16 v[100:103], v[184:187], v[152:155], v[100:103]
	v_mfma_f32_16x16x32_bf16 v[92:95], v[176:179], v[160:163], v[92:95]
	v_mfma_f32_16x16x32_bf16 v[84:87], v[184:187], v[160:163], v[84:87]
	v_mfma_f32_16x16x32_bf16 v[76:79], v[176:179], v[168:171], v[76:79]
	v_mfma_f32_16x16x32_bf16 v[68:71], v[184:187], v[168:171], v[68:71]
	v_mfma_f32_16x16x32_bf16 v[124:127], v[180:183], v[148:151], v[124:127]
	v_mfma_f32_16x16x32_bf16 v[116:119], v[202:205], v[148:151], v[116:119]
	v_mfma_f32_16x16x32_bf16 v[108:111], v[180:183], v[156:159], v[108:111]
	v_mfma_f32_16x16x32_bf16 v[100:103], v[202:205], v[156:159], v[100:103]
	v_mfma_f32_16x16x32_bf16 v[92:95], v[180:183], v[164:167], v[92:95]
	v_mfma_f32_16x16x32_bf16 v[84:87], v[202:205], v[164:167], v[84:87]
	v_mfma_f32_16x16x32_bf16 v[76:79], v[180:183], v[172:175], v[76:79]
	v_mfma_f32_16x16x32_bf16 v[68:71], v[202:205], v[172:175], v[68:71]
	s_mov_b32 m0, s50
	v_lshl_add_u64 v[210:211], s[4:5], 0, v[192:193]
	s_barrier
	ds_read_b128 v[144:147], v221 offset:16384
	ds_read_b128 v[148:151], v221 offset:17408
	ds_read_b128 v[152:155], v221 offset:18432
	ds_read_b128 v[156:159], v221 offset:19456
	ds_read_b128 v[160:163], v221 offset:20480
	ds_read_b128 v[164:167], v221 offset:21504
	ds_read_b128 v[168:171], v221 offset:22528
	ds_read_b128 v[172:175], v221 offset:23552
	global_load_lds_dwordx4 v[210:211], off
	v_lshl_add_u64 v[212:213], s[4:5], 0, v[194:195]
	s_mov_b32 m0, s51
	s_nop 0
	global_load_lds_dwordx4 v[212:213], off
	s_barrier
	s_waitcnt lgkmcnt(0)
	s_waitcnt lgkmcnt(0)
	v_mfma_f32_16x16x32_bf16 v[60:63], v[128:131], v[144:147], v[60:63]
	v_mfma_f32_16x16x32_bf16 v[52:55], v[136:139], v[144:147], v[52:55]
	v_mfma_f32_16x16x32_bf16 v[44:47], v[128:131], v[152:155], v[44:47]
	v_mfma_f32_16x16x32_bf16 v[36:39], v[136:139], v[152:155], v[36:39]
	v_mfma_f32_16x16x32_bf16 v[28:31], v[128:131], v[160:163], v[28:31]
	v_mfma_f32_16x16x32_bf16 v[20:23], v[136:139], v[160:163], v[20:23]
	v_mfma_f32_16x16x32_bf16 v[12:15], v[128:131], v[168:171], v[12:15]
	v_mfma_f32_16x16x32_bf16 v[4:7], v[136:139], v[168:171], v[4:7]
	v_mfma_f32_16x16x32_bf16 v[60:63], v[132:135], v[148:151], v[60:63]
	v_mfma_f32_16x16x32_bf16 v[52:55], v[140:143], v[148:151], v[52:55]
	v_mfma_f32_16x16x32_bf16 v[44:47], v[132:135], v[156:159], v[44:47]
	v_mfma_f32_16x16x32_bf16 v[36:39], v[140:143], v[156:159], v[36:39]
	v_mfma_f32_16x16x32_bf16 v[28:31], v[132:135], v[164:167], v[28:31]
	v_mfma_f32_16x16x32_bf16 v[20:23], v[140:143], v[164:167], v[20:23]
	v_mfma_f32_16x16x32_bf16 v[12:15], v[132:135], v[172:175], v[12:15]
	v_mfma_f32_16x16x32_bf16 v[4:7], v[140:143], v[172:175], v[4:7]
	s_barrier
; #define PG8_STAGE(bufoff, gbase, voff) do { _Pragma("unroll") for (int _i = 0; _i < 2; ++_i) \
;         __builtin_amdgcn_global_load_lds((const unsigned*)((const char*)(gbase) + (voff)[_i]), (LAS unsigned*)(lds + (bufoff) + ldsw + _i * 8192), 16, 0, 0); } while (0)
; #define PG8_LDA(dst, b, h) do { _Pragma("unroll") for (int m = 0; m < 4; ++m) _Pragma("unroll") for (int k = 0; k < 2; ++k) dst[m][k] = *(const LAS bf16x8*)(lds + PG8_SA(b, h) + aoff + m * 2048 + k * 1024); } while (0)
; #define PG8_LDB(dst, b, h) do { _Pragma("unroll") for (int n = 0; n < 2; ++n) _Pragma("unroll") for (int k = 0; k < 2; ++k) dst[n][k] = *(const LAS bf16x8*)(lds + PG8_SB(b, h) + boff + n * 2048 + k * 1024); } while (0)
; #define PG8_MMA(ai, bj, At, Bt) do { __builtin_amdgcn_s_setprio(1); _Pragma("unroll") for (int m = 0; m < 4; ++m) _Pragma("unroll") for (int n = 0; n < 2; ++n) _Pragma("unroll") for (int k = 0; k < 2; ++k) \
;         acc[ai][bj][m][n] = __builtin_amdgcn_mfma_f32_16x16x32_bf16(Bt[n][k], At[m][k], acc[ai][bj][m][n], 0, 0, 0); __builtin_amdgcn_s_setprio(0); } while (0)
; #define PG8_WAIT_V(n) asm volatile("s_waitcnt vmcnt(" #n ")" ::: "memory")
; #define PG8_WAIT_L(n) asm volatile("s_waitcnt lgkmcnt(" #n ")" ::: "memory")
; #define PG8_BAR __builtin_amdgcn_s_barrier()
; #define PG8_SCHED __builtin_amdgcn_sched_barrier(0)
; template <class Epi, class Sched>
; __device__ __forceinline__ void gemm_phase(LAS unsigned char* lds, const Gemm g, const Sched& S, const Epi& E) {
;     ...
;             PG8_STAGE(PG8_SB(0, 1), b2 + hstep, voffB);
;             PG8_WAIT_V(6); PG8_BAR; PG8_MMA(1, 1, At, B1); PG8_BAR;
;             PG8_LDB(B0, 1, 0); PG8_SCHED; PG8_LDA(At, 1, 0); PG8_STAGE(PG8_SA(0, 1), a2 + hstep, voffA);
;             PG8_WAIT_L(8); PG8_BAR; PG8_WAIT_L(0); PG8_MMA(0, 0, At, B0); PG8_BAR; PG8_SCHED;
;             PG8_LDB(B1, 1, 1); PG8_STAGE(PG8_SB(1, 0), b3, voffB);
	s_add_u32 s28, s28, s20
	s_addc_u32 s29, s29, s21
	s_add_i32 s31, s33, s34
	v_lshl_add_u64 v[222:223], s[28:29], 0, v[192:193]
	s_mov_b32 m0, s31
	v_lshl_add_u64 v[224:225], s[28:29], 0, v[194:195]
	global_load_lds_dwordx4 v[222:223], off
	s_add_i32 m0, s31, 0x2000
	s_nop 0
	global_load_lds_dwordx4 v[224:225], off
	s_waitcnt vmcnt(6)
	s_barrier
	v_mfma_f32_16x16x32_bf16 v[56:59], v[176:179], v[144:147], v[56:59]
	v_mfma_f32_16x16x32_bf16 v[48:51], v[184:187], v[144:147], v[48:51]
	v_mfma_f32_16x16x32_bf16 v[40:43], v[176:179], v[152:155], v[40:43]
	v_mfma_f32_16x16x32_bf16 v[32:35], v[184:187], v[152:155], v[32:35]
	v_mfma_f32_16x16x32_bf16 v[24:27], v[176:179], v[160:163], v[24:27]
	v_mfma_f32_16x16x32_bf16 v[16:19], v[184:187], v[160:163], v[16:19]
	v_mfma_f32_16x16x32_bf16 v[8:11], v[176:179], v[168:171], v[8:11]
	v_mfma_f32_16x16x32_bf16 v[0:3], v[184:187], v[168:171], v[0:3]
	v_mfma_f32_16x16x32_bf16 v[56:59], v[180:183], v[148:151], v[56:59]
	v_mfma_f32_16x16x32_bf16 v[48:51], v[202:205], v[148:151], v[48:51]
	v_mfma_f32_16x16x32_bf16 v[40:43], v[180:183], v[156:159], v[40:43]
	v_mfma_f32_16x16x32_bf16 v[32:35], v[202:205], v[156:159], v[32:35]
	v_mfma_f32_16x16x32_bf16 v[24:27], v[180:183], v[164:167], v[24:27]
	v_mfma_f32_16x16x32_bf16 v[16:19], v[202:205], v[164:167], v[16:19]
	v_mfma_f32_16x16x32_bf16 v[8:11], v[180:183], v[172:175], v[8:11]
	v_mfma_f32_16x16x32_bf16 v[0:3], v[202:205], v[172:175], v[0:3]
	s_add_i32 s28, 0, 0x18000
	v_add_u32_e32 v140, s28, v214
	s_barrier
	ds_read_b128 v[128:131], v140
	ds_read_b128 v[132:135], v140 offset:1024
	ds_read_b128 v[136:139], v140 offset:2048
	ds_read_b128 v[140:143], v140 offset:3072
	s_add_u32 s4, s4, s20
	s_addc_u32 s5, s5, s21
	s_mov_b32 m0, s60
	v_lshl_add_u64 v[176:177], s[4:5], 0, v[192:193]
	ds_read_b128 v[144:147], v221 offset:32768
	ds_read_b128 v[148:151], v221 offset:33792
	ds_read_b128 v[152:155], v221 offset:34816
	ds_read_b128 v[156:159], v221 offset:35840
	ds_read_b128 v[160:163], v221 offset:36864
	ds_read_b128 v[164:167], v221 offset:37888
	ds_read_b128 v[168:171], v221 offset:38912
	ds_read_b128 v[172:175], v221 offset:39936
	global_load_lds_dwordx4 v[176:177], off
	v_lshl_add_u64 v[176:177], s[4:5], 0, v[194:195]
	s_mov_b32 m0, s61
	s_nop 0
	global_load_lds_dwordx4 v[176:177], off
	s_waitcnt lgkmcnt(8)
	s_barrier
	s_waitcnt lgkmcnt(0)
	s_waitcnt lgkmcnt(0)
	v_mfma_f32_16x16x32_bf16 v[120:123], v[128:131], v[144:147], v[120:123]
	v_mfma_f32_16x16x32_bf16 v[112:115], v[136:139], v[144:147], v[112:115]
	v_mfma_f32_16x16x32_bf16 v[104:107], v[128:131], v[152:155], v[104:107]
	v_mfma_f32_16x16x32_bf16 v[96:99], v[136:139], v[152:155], v[96:99]
	v_mfma_f32_16x16x32_bf16 v[88:91], v[128:131], v[160:163], v[88:91]
	v_mfma_f32_16x16x32_bf16 v[80:83], v[136:139], v[160:163], v[80:83]
	v_mfma_f32_16x16x32_bf16 v[72:75], v[128:131], v[168:171], v[72:75]
	v_mfma_f32_16x16x32_bf16 v[64:67], v[136:139], v[168:171], v[64:67]
	v_mfma_f32_16x16x32_bf16 v[120:123], v[132:135], v[148:151], v[120:123]
	v_mfma_f32_16x16x32_bf16 v[112:115], v[140:143], v[148:151], v[112:115]
	v_mfma_f32_16x16x32_bf16 v[104:107], v[132:135], v[156:159], v[104:107]
	v_mfma_f32_16x16x32_bf16 v[96:99], v[140:143], v[156:159], v[96:99]
	v_mfma_f32_16x16x32_bf16 v[88:91], v[132:135], v[164:167], v[88:91]
	v_mfma_f32_16x16x32_bf16 v[80:83], v[140:143], v[164:167], v[80:83]
	v_mfma_f32_16x16x32_bf16 v[72:75], v[132:135], v[172:175], v[72:75]
	v_mfma_f32_16x16x32_bf16 v[64:67], v[140:143], v[172:175], v[64:67]
	s_barrier
	s_add_i32 s4, 0, 0x1c000
	s_add_i32 s5, s28, s34
	v_add_u32_e32 v188, s4, v214
	v_lshl_add_u64 v[206:207], v[206:207], 0, s[64:65]
	s_mov_b32 m0, s5
	ds_read_b128 v[176:179], v188
	ds_read_b128 v[180:183], v188 offset:1024
	ds_read_b128 v[184:187], v188 offset:2048
	ds_read_b128 v[202:205], v188 offset:3072
	global_load_lds_dwordx4 v[206:207], off
	v_lshl_add_u64 v[206:207], v[208:209], 0, s[64:65]
	s_add_i32 m0, s5, 0x2000
	s_nop 0
	global_load_lds_dwordx4 v[206:207], off
	s_barrier
; #define PG8_STAGE(bufoff, gbase, voff) do { _Pragma("unroll") for (int _i = 0; _i < 2; ++_i) \
;         __builtin_amdgcn_global_load_lds((const unsigned*)((const char*)(gbase) + (voff)[_i]), (LAS unsigned*)(lds + (bufoff) + ldsw + _i * 8192), 16, 0, 0); } while (0)
; #define PG8_LDA(dst, b, h) do { _Pragma("unroll") for (int m = 0; m < 4; ++m) _Pragma("unroll") for (int k = 0; k < 2; ++k) dst[m][k] = *(const LAS bf16x8*)(lds + PG8_SA(b, h) + aoff + m * 2048 + k * 1024); } while (0)
; #define PG8_MMA(ai, bj, At, Bt) do { __builtin_amdgcn_s_setprio(1); _Pragma("unroll") for (int m = 0; m < 4; ++m) _Pragma("unroll") for (int n = 0; n < 2; ++n) _Pragma("unroll") for (int k = 0; k < 2; ++k) \
;         acc[ai][bj][m][n] = __builtin_amdgcn_mfma_f32_16x16x32_bf16(Bt[n][k], At[m][k], acc[ai][bj][m][n], 0, 0, 0); __builtin_amdgcn_s_setprio(0); } while (0)
; #define PG8_WAIT_V(n) asm volatile("s_waitcnt vmcnt(" #n ")" ::: "memory")
; #define PG8_WAIT_L(n) asm volatile("s_waitcnt lgkmcnt(" #n ")" ::: "memory")
; #define PG8_BAR __builtin_amdgcn_s_barrier()
; #define PG8_SCHED __builtin_amdgcn_sched_barrier(0)
; template <class Epi, class Sched>
; __device__ __forceinline__ void gemm_phase(LAS unsigned char* lds, const Gemm g, const Sched& S, const Epi& E) {
;     ...
;             PG8_BAR; PG8_WAIT_L(0); PG8_MMA(0, 1, At, B1); PG8_BAR;
;             PG8_LDA(At, 1, 1); PG8_STAGE(PG8_SA(1, 0), a3, voffA);
;             PG8_BAR; PG8_WAIT_L(0); PG8_MMA(1, 0, At, B0); PG8_BAR; PG8_SCHED;
;             PG8_STAGE(PG8_SB(1, 1), b3 + hstep, voffB);
;             PG8_WAIT_V(6); PG8_BAR; PG8_MMA(1, 1, At, B1); PG8_BAR;
;         }
;         E(acc, cur, wr, wc, fr, fq, lds, ui);
;         if (!has_next) break;
	s_waitcnt lgkmcnt(0)
	s_waitcnt lgkmcnt(0)
	v_mfma_f32_16x16x32_bf16 v[124:127], v[176:179], v[144:147], v[124:127]
	v_mfma_f32_16x16x32_bf16 v[116:119], v[184:187], v[144:147], v[116:119]
	v_mfma_f32_16x16x32_bf16 v[108:111], v[176:179], v[152:155], v[108:111]
	v_mfma_f32_16x16x32_bf16 v[100:103], v[184:187], v[152:155], v[100:103]
	v_mfma_f32_16x16x32_bf16 v[92:95], v[176:179], v[160:163], v[92:95]
	v_mfma_f32_16x16x32_bf16 v[84:87], v[184:187], v[160:163], v[84:87]
	v_mfma_f32_16x16x32_bf16 v[76:79], v[176:179], v[168:171], v[76:79]
	v_mfma_f32_16x16x32_bf16 v[68:71], v[184:187], v[168:171], v[68:71]
	v_mfma_f32_16x16x32_bf16 v[124:127], v[180:183], v[148:151], v[124:127]
	v_mfma_f32_16x16x32_bf16 v[116:119], v[202:205], v[148:151], v[116:119]
	v_mfma_f32_16x16x32_bf16 v[108:111], v[180:183], v[156:159], v[108:111]
	v_mfma_f32_16x16x32_bf16 v[100:103], v[202:205], v[156:159], v[100:103]
	v_mfma_f32_16x16x32_bf16 v[92:95], v[180:183], v[164:167], v[92:95]
	v_mfma_f32_16x16x32_bf16 v[84:87], v[202:205], v[164:167], v[84:87]
	v_mfma_f32_16x16x32_bf16 v[76:79], v[180:183], v[172:175], v[76:79]
	v_mfma_f32_16x16x32_bf16 v[68:71], v[202:205], v[172:175], v[68:71]
	s_mov_b32 m0, s62
	v_lshl_add_u64 v[206:207], v[210:211], 0, s[64:65]
	s_barrier
	ds_read_b128 v[144:147], v221 offset:49152
	ds_read_b128 v[148:151], v221 offset:50176
	ds_read_b128 v[152:155], v221 offset:51200
	ds_read_b128 v[156:159], v221 offset:52224
	ds_read_b128 v[160:163], v221 offset:53248
	ds_read_b128 v[164:167], v221 offset:54272
	ds_read_b128 v[168:171], v221 offset:55296
	ds_read_b128 v[172:175], v221 offset:56320
	global_load_lds_dwordx4 v[206:207], off
	v_lshl_add_u64 v[206:207], v[212:213], 0, s[64:65]
	s_mov_b32 m0, s63
	s_nop 0
	global_load_lds_dwordx4 v[206:207], off
	s_barrier
	s_waitcnt lgkmcnt(0)
	s_waitcnt lgkmcnt(0)
	v_mfma_f32_16x16x32_bf16 v[60:63], v[128:131], v[144:147], v[60:63]
	v_mfma_f32_16x16x32_bf16 v[52:55], v[136:139], v[144:147], v[52:55]
	v_mfma_f32_16x16x32_bf16 v[44:47], v[128:131], v[152:155], v[44:47]
	v_mfma_f32_16x16x32_bf16 v[36:39], v[136:139], v[152:155], v[36:39]
	v_mfma_f32_16x16x32_bf16 v[28:31], v[128:131], v[160:163], v[28:31]
	v_mfma_f32_16x16x32_bf16 v[20:23], v[136:139], v[160:163], v[20:23]
	v_mfma_f32_16x16x32_bf16 v[12:15], v[128:131], v[168:171], v[12:15]
	v_mfma_f32_16x16x32_bf16 v[4:7], v[136:139], v[168:171], v[4:7]
	v_mfma_f32_16x16x32_bf16 v[60:63], v[132:135], v[148:151], v[60:63]
	v_mfma_f32_16x16x32_bf16 v[52:55], v[140:143], v[148:151], v[52:55]
	v_mfma_f32_16x16x32_bf16 v[44:47], v[132:135], v[156:159], v[44:47]
	v_mfma_f32_16x16x32_bf16 v[36:39], v[140:143], v[156:159], v[36:39]
	v_mfma_f32_16x16x32_bf16 v[28:31], v[132:135], v[164:167], v[28:31]
	v_mfma_f32_16x16x32_bf16 v[20:23], v[140:143], v[164:167], v[20:23]
	v_mfma_f32_16x16x32_bf16 v[12:15], v[132:135], v[172:175], v[12:15]
	v_mfma_f32_16x16x32_bf16 v[4:7], v[140:143], v[172:175], v[4:7]
	s_barrier
	s_add_i32 s4, s4, s34
	v_lshl_add_u64 v[128:129], v[222:223], 0, s[64:65]
	s_mov_b32 m0, s4
	s_nop 0
	global_load_lds_dwordx4 v[128:129], off
	v_lshl_add_u64 v[128:129], v[224:225], 0, s[64:65]
	s_add_i32 m0, s4, 0x2000
	s_nop 0
	global_load_lds_dwordx4 v[128:129], off
	s_waitcnt vmcnt(6)
	s_barrier
	v_mfma_f32_16x16x32_bf16 v[56:59], v[176:179], v[144:147], v[56:59]
	v_mfma_f32_16x16x32_bf16 v[48:51], v[184:187], v[144:147], v[48:51]
	v_mfma_f32_16x16x32_bf16 v[40:43], v[176:179], v[152:155], v[40:43]
	v_mfma_f32_16x16x32_bf16 v[32:35], v[184:187], v[152:155], v[32:35]
	v_mfma_f32_16x16x32_bf16 v[24:27], v[176:179], v[160:163], v[24:27]
	v_mfma_f32_16x16x32_bf16 v[16:19], v[184:187], v[160:163], v[16:19]
	v_mfma_f32_16x16x32_bf16 v[8:11], v[176:179], v[168:171], v[8:11]
	v_mfma_f32_16x16x32_bf16 v[0:3], v[184:187], v[168:171], v[0:3]
	v_mfma_f32_16x16x32_bf16 v[56:59], v[180:183], v[148:151], v[56:59]
	v_mfma_f32_16x16x32_bf16 v[48:51], v[202:205], v[148:151], v[48:51]
	v_mfma_f32_16x16x32_bf16 v[40:43], v[180:183], v[156:159], v[40:43]
	v_mfma_f32_16x16x32_bf16 v[32:35], v[202:205], v[156:159], v[32:35]
	v_mfma_f32_16x16x32_bf16 v[24:27], v[180:183], v[164:167], v[24:27]
	v_mfma_f32_16x16x32_bf16 v[16:19], v[202:205], v[164:167], v[16:19]
	v_mfma_f32_16x16x32_bf16 v[8:11], v[180:183], v[172:175], v[8:11]
	v_mfma_f32_16x16x32_bf16 v[0:3], v[202:205], v[172:175], v[0:3]
	s_add_u32 s75, s75, 0x100
	s_addc_u32 s76, s76, 0
	s_add_u32 s0, s0, 0x100
	s_addc_u32 s1, s1, 0
	s_cmp_ge_i32 s30, s13
	s_mov_b32 s4, s30
	s_barrier
	s_cbranch_scc0 .LBB0_339
	s_mov_b32 s33, 0x200000
	s_cmp_lt_i32 s15, 2
	s_cbranch_scc1 .LBB0_345
